# E49: up-projection GEMM epilogues: canonicalise+clamp pair (max(x,x); max(0,t)) folded into one max(0,x) per element, 128 fewer VALU per thread per tile; on E41
# baseline (speedup 1.0000x reference)
.LBB0_823:
	v_lshl_add_u32 v150, s36, 8, v3
	v_ashrrev_i32_e32 v151, 31, v150
	v_lshlrev_b64 v[152:153], 13, v[150:151]
	ds_read_b32 v151, v155
	v_max_f32_e32 v124, 0, v124
	v_max_f32_e32 v125, 0, v125
	v_max_f32_e32 v126, 0, v126
	s_waitcnt lgkmcnt(0)
	v_mul_f32_e32 v124, v124, v151
	v_mul_f32_e32 v161, v124, v124
	v_max_f32_e32 v124, 0, v129
	v_mul_f32_e32 v125, v125, v151
	v_mul_f32_e32 v126, v126, v151
	v_lshl_or_b32 v148, s66, 8, v157
	v_max_f32_e32 v128, 0, v128
	v_mul_f32_e32 v129, v125, v125
	v_max_f32_e32 v125, 0, v130
	v_mul_f32_e32 v130, v126, v126
	v_max_f32_e32 v126, 0, v131
	v_max_f32_e32 v127, 0, v127
	v_ashrrev_i32_e32 v149, 31, v148
	v_mul_f32_e32 v124, v124, v151
	v_max_f32_e32 v116, 0, v116
	v_max_f32_e32 v117, 0, v117
	v_max_f32_e32 v118, 0, v118
	v_lshl_add_u64 v[162:163], s[10:11], 0, v[152:153]
	v_lshlrev_b64 v[152:153], 1, v[148:149]
	v_mul_f32_e32 v128, v128, v151
	v_mul_f32_e32 v124, v124, v124
	v_mul_f32_e32 v125, v125, v151
	v_mul_f32_e32 v126, v126, v151
	v_mul_f32_e32 v127, v127, v151
	v_lshl_add_u64 v[148:149], v[162:163], 0, v[152:153]
	v_mul_f32_e32 v128, v128, v128
	v_mul_f32_e32 v125, v125, v125
	v_mul_f32_e32 v126, v126, v126
	v_mul_f32_e32 v127, v127, v127
	v_cvt_pk_bf16_f32 v124, v128, v124
	v_mul_f32_e32 v116, v116, v151
	v_mul_f32_e32 v117, v117, v151
	v_mul_f32_e32 v118, v118, v151
	v_cvt_pk_bf16_f32 v125, v125, v126
	v_cvt_pk_bf16_f32 v126, v161, v129
	v_cvt_pk_bf16_f32 v127, v130, v127
	global_store_dwordx4 v[148:149], v[124:127], off sc1
	v_max_f32_e32 v120, 0, v120
	v_max_f32_e32 v119, 0, v119
	v_mul_f32_e32 v124, v116, v116
	v_max_f32_e32 v116, 0, v121
	v_mul_f32_e32 v121, v117, v117
	v_max_f32_e32 v117, 0, v122
	v_mul_f32_e32 v122, v118, v118
	v_max_f32_e32 v118, 0, v123
	v_mul_f32_e32 v116, v116, v151
	v_mul_f32_e32 v117, v117, v151
	v_mul_f32_e32 v118, v118, v151
	v_mul_f32_e32 v120, v120, v151
	v_mul_f32_e32 v116, v116, v116
	v_mul_f32_e32 v117, v117, v117
	v_mul_f32_e32 v119, v119, v151
	v_mul_f32_e32 v118, v118, v118
	v_mul_f32_e32 v120, v120, v120
	v_mul_f32_e32 v119, v119, v119
	v_cvt_pk_bf16_f32 v116, v120, v116
	v_cvt_pk_bf16_f32 v117, v117, v118
	v_cvt_pk_bf16_f32 v118, v124, v121
	v_cvt_pk_bf16_f32 v119, v122, v119
	global_store_dwordx4 v[148:149], v[116:119], off offset:256 sc1
	ds_read_b32 v118, v155 offset:64
	v_max_f32_e32 v108, 0, v108
	v_max_f32_e32 v109, 0, v109
	v_max_f32_e32 v110, 0, v110
	s_waitcnt lgkmcnt(0)
	v_mul_f32_e32 v108, v108, v118
	v_or_b32_e32 v116, 16, v150
	v_mul_f32_e32 v119, v108, v108
	v_max_f32_e32 v108, 0, v113
	v_mul_f32_e32 v109, v109, v118
	v_mul_f32_e32 v110, v110, v118
	v_ashrrev_i32_e32 v117, 31, v116
	v_max_f32_e32 v112, 0, v112
	v_mul_f32_e32 v113, v109, v109
	v_max_f32_e32 v109, 0, v114
	v_mul_f32_e32 v114, v110, v110
	v_max_f32_e32 v110, 0, v115
	v_max_f32_e32 v111, 0, v111
	v_lshlrev_b64 v[116:117], 13, v[116:117]
	v_mul_f32_e32 v108, v108, v118
	v_max_f32_e32 v100, 0, v100
	v_max_f32_e32 v101, 0, v101
	v_max_f32_e32 v102, 0, v102
	v_lshl_add_u64 v[116:117], s[10:11], 0, v[116:117]
	v_mul_f32_e32 v112, v112, v118
	v_mul_f32_e32 v108, v108, v108
	v_mul_f32_e32 v109, v109, v118
	v_mul_f32_e32 v110, v110, v118
	v_mul_f32_e32 v111, v111, v118
	v_lshl_add_u64 v[116:117], v[116:117], 0, v[152:153]
	v_mul_f32_e32 v112, v112, v112
	v_mul_f32_e32 v109, v109, v109
	v_mul_f32_e32 v110, v110, v110
	v_mul_f32_e32 v111, v111, v111
	v_cvt_pk_bf16_f32 v108, v112, v108
	v_mul_f32_e32 v100, v100, v118
	v_mul_f32_e32 v101, v101, v118
	v_mul_f32_e32 v102, v102, v118
	v_cvt_pk_bf16_f32 v109, v109, v110
	v_cvt_pk_bf16_f32 v110, v119, v113
	v_cvt_pk_bf16_f32 v111, v114, v111
	global_store_dwordx4 v[116:117], v[108:111], off sc1
	v_max_f32_e32 v104, 0, v104
	v_max_f32_e32 v103, 0, v103
	v_mul_f32_e32 v108, v100, v100
	v_max_f32_e32 v100, 0, v105
	v_mul_f32_e32 v105, v101, v101
	v_max_f32_e32 v101, 0, v106
	v_mul_f32_e32 v106, v102, v102
	v_max_f32_e32 v102, 0, v107
	v_mul_f32_e32 v100, v100, v118
	v_mul_f32_e32 v101, v101, v118
	v_mul_f32_e32 v102, v102, v118
	v_mul_f32_e32 v104, v104, v118
	v_mul_f32_e32 v100, v100, v100
	v_mul_f32_e32 v101, v101, v101
	v_mul_f32_e32 v103, v103, v118
	v_mul_f32_e32 v102, v102, v102
	v_mul_f32_e32 v104, v104, v104
	v_mul_f32_e32 v103, v103, v103
	v_cvt_pk_bf16_f32 v100, v104, v100
	v_cvt_pk_bf16_f32 v101, v101, v102
	v_cvt_pk_bf16_f32 v102, v108, v105
	v_cvt_pk_bf16_f32 v103, v106, v103
	global_store_dwordx4 v[116:117], v[100:103], off offset:256 sc1
	ds_read_b32 v102, v155 offset:128
	v_max_f32_e32 v92, 0, v92
	v_max_f32_e32 v93, 0, v93
	v_max_f32_e32 v94, 0, v94
	s_waitcnt lgkmcnt(0)
	v_mul_f32_e32 v92, v92, v102
	v_or_b32_e32 v100, 32, v150
	v_mul_f32_e32 v103, v92, v92
	v_max_f32_e32 v92, 0, v97
	v_mul_f32_e32 v93, v93, v102
	v_mul_f32_e32 v94, v94, v102
	v_ashrrev_i32_e32 v101, 31, v100
	v_max_f32_e32 v96, 0, v96
	v_mul_f32_e32 v97, v93, v93
	v_max_f32_e32 v93, 0, v98
	v_mul_f32_e32 v98, v94, v94
	v_max_f32_e32 v94, 0, v99
	v_max_f32_e32 v95, 0, v95
	v_lshlrev_b64 v[100:101], 13, v[100:101]
	v_mul_f32_e32 v92, v92, v102
	v_max_f32_e32 v84, 0, v84
	v_max_f32_e32 v85, 0, v85
	v_max_f32_e32 v86, 0, v86
	v_lshl_add_u64 v[100:101], s[10:11], 0, v[100:101]
	v_mul_f32_e32 v96, v96, v102
	v_mul_f32_e32 v92, v92, v92
	v_mul_f32_e32 v93, v93, v102
	v_mul_f32_e32 v94, v94, v102
	v_mul_f32_e32 v95, v95, v102
	v_lshl_add_u64 v[100:101], v[100:101], 0, v[152:153]
	v_mul_f32_e32 v96, v96, v96
	v_mul_f32_e32 v93, v93, v93
	v_mul_f32_e32 v94, v94, v94
	v_mul_f32_e32 v95, v95, v95
	v_cvt_pk_bf16_f32 v92, v96, v92
	v_mul_f32_e32 v84, v84, v102
	v_mul_f32_e32 v85, v85, v102
	v_mul_f32_e32 v86, v86, v102
	v_cvt_pk_bf16_f32 v93, v93, v94
	v_cvt_pk_bf16_f32 v94, v103, v97
	v_cvt_pk_bf16_f32 v95, v98, v95
	global_store_dwordx4 v[100:101], v[92:95], off sc1
	v_max_f32_e32 v88, 0, v88
	v_max_f32_e32 v87, 0, v87
	v_mul_f32_e32 v92, v84, v84
	v_max_f32_e32 v84, 0, v89
	v_mul_f32_e32 v89, v85, v85
	v_max_f32_e32 v85, 0, v90
	v_mul_f32_e32 v90, v86, v86
	v_max_f32_e32 v86, 0, v91
	v_mul_f32_e32 v84, v84, v102
	v_mul_f32_e32 v85, v85, v102
	v_mul_f32_e32 v86, v86, v102
	v_mul_f32_e32 v88, v88, v102
	v_mul_f32_e32 v84, v84, v84
	v_mul_f32_e32 v85, v85, v85
	v_mul_f32_e32 v87, v87, v102
	v_mul_f32_e32 v86, v86, v86
	v_mul_f32_e32 v88, v88, v88
	v_mul_f32_e32 v87, v87, v87
	v_cvt_pk_bf16_f32 v84, v88, v84
	v_cvt_pk_bf16_f32 v85, v85, v86
	v_cvt_pk_bf16_f32 v86, v92, v89
	v_cvt_pk_bf16_f32 v87, v90, v87
	global_store_dwordx4 v[100:101], v[84:87], off offset:256 sc1
	ds_read_b32 v86, v155 offset:192
	v_max_f32_e32 v76, 0, v76
	v_max_f32_e32 v77, 0, v77
	v_max_f32_e32 v78, 0, v78
	s_waitcnt lgkmcnt(0)
	v_mul_f32_e32 v76, v76, v86
	v_or_b32_e32 v84, 48, v150
	v_mul_f32_e32 v87, v76, v76
	v_max_f32_e32 v76, 0, v81
	v_mul_f32_e32 v77, v77, v86
	v_mul_f32_e32 v78, v78, v86
	v_ashrrev_i32_e32 v85, 31, v84
	v_max_f32_e32 v80, 0, v80
	v_mul_f32_e32 v81, v77, v77
	v_max_f32_e32 v77, 0, v82
	v_mul_f32_e32 v82, v78, v78
	v_max_f32_e32 v78, 0, v83
	v_max_f32_e32 v79, 0, v79
	v_lshlrev_b64 v[84:85], 13, v[84:85]
	v_mul_f32_e32 v76, v76, v86
	v_max_f32_e32 v68, 0, v68
	v_max_f32_e32 v69, 0, v69
	v_max_f32_e32 v70, 0, v70
	v_lshl_add_u64 v[84:85], s[10:11], 0, v[84:85]
	v_mul_f32_e32 v80, v80, v86
	v_mul_f32_e32 v76, v76, v76
	v_mul_f32_e32 v77, v77, v86
	v_mul_f32_e32 v78, v78, v86
	v_mul_f32_e32 v79, v79, v86
	v_lshl_add_u64 v[84:85], v[84:85], 0, v[152:153]
	v_mul_f32_e32 v80, v80, v80
	v_mul_f32_e32 v77, v77, v77
	v_mul_f32_e32 v78, v78, v78
	v_mul_f32_e32 v79, v79, v79
	v_cvt_pk_bf16_f32 v76, v80, v76
	v_mul_f32_e32 v68, v68, v86
	v_mul_f32_e32 v69, v69, v86
	v_mul_f32_e32 v70, v70, v86
	v_cvt_pk_bf16_f32 v77, v77, v78
	v_cvt_pk_bf16_f32 v78, v87, v81
	v_cvt_pk_bf16_f32 v79, v82, v79
	global_store_dwordx4 v[84:85], v[76:79], off sc1
	v_max_f32_e32 v72, 0, v72
	v_max_f32_e32 v71, 0, v71
	v_mul_f32_e32 v76, v68, v68
	v_max_f32_e32 v68, 0, v73
	v_mul_f32_e32 v73, v69, v69
	v_max_f32_e32 v69, 0, v74
	v_mul_f32_e32 v74, v70, v70
	v_max_f32_e32 v70, 0, v75
	v_mul_f32_e32 v72, v72, v86
	v_mul_f32_e32 v68, v68, v86
	v_mul_f32_e32 v69, v69, v86
	v_mul_f32_e32 v70, v70, v86
	v_mul_f32_e32 v71, v71, v86
	v_mul_f32_e32 v72, v72, v72
	v_mul_f32_e32 v68, v68, v68
	v_mul_f32_e32 v69, v69, v69
	v_mul_f32_e32 v70, v70, v70
	v_mul_f32_e32 v71, v71, v71
	v_cvt_pk_bf16_f32 v68, v72, v68
	v_cvt_pk_bf16_f32 v69, v69, v70
	v_cvt_pk_bf16_f32 v70, v76, v73
	v_cvt_pk_bf16_f32 v71, v74, v71
	ds_read_b32 v72, v156
	v_max_f32_e32 v60, 0, v60
	v_max_f32_e32 v61, 0, v61
	v_max_f32_e32 v62, 0, v62
	s_waitcnt lgkmcnt(0)
	v_mul_f32_e32 v60, v60, v72
	global_store_dwordx4 v[84:85], v[68:71], off offset:256 sc1
	v_max_f32_e32 v64, 0, v64
	v_mul_f32_e32 v61, v61, v72
	v_mul_f32_e32 v70, v60, v60
	v_max_f32_e32 v60, 0, v65
	v_mul_f32_e32 v62, v62, v72
	v_mul_f32_e32 v65, v61, v61
	v_max_f32_e32 v61, 0, v66
	v_mul_f32_e32 v66, v62, v62
	v_max_f32_e32 v62, 0, v67
	v_mul_f32_e32 v64, v64, v72
	v_mul_f32_e32 v60, v60, v72
	v_max_f32_e32 v63, 0, v63
	v_mul_f32_e32 v64, v64, v64
	v_mul_f32_e32 v60, v60, v60
	v_mul_f32_e32 v61, v61, v72
	v_mul_f32_e32 v62, v62, v72
	v_max_f32_e32 v52, 0, v52
	v_max_f32_e32 v53, 0, v53
	v_max_f32_e32 v54, 0, v54
	v_mul_f32_e32 v61, v61, v61
	v_mul_f32_e32 v63, v63, v72
	v_mul_f32_e32 v62, v62, v62
	v_cvt_pk_bf16_f32 v60, v64, v60
	v_add_co_u32_e32 v64, vcc, s60, v148
	v_mul_f32_e32 v63, v63, v63
	v_cvt_pk_bf16_f32 v61, v61, v62
	v_cvt_pk_bf16_f32 v62, v70, v65
	v_addc_co_u32_e32 v65, vcc, 0, v149, vcc
	v_mul_f32_e32 v52, v52, v72
	v_mul_f32_e32 v53, v53, v72
	v_mul_f32_e32 v54, v54, v72
	v_cvt_pk_bf16_f32 v63, v66, v63
	global_store_dwordx4 v[64:65], v[60:63], off sc1
	v_max_f32_e32 v56, 0, v56
	v_max_f32_e32 v55, 0, v55
	v_mul_f32_e32 v60, v52, v52
	v_max_f32_e32 v52, 0, v57
	v_mul_f32_e32 v57, v53, v53
	v_max_f32_e32 v53, 0, v58
	v_mul_f32_e32 v58, v54, v54
	v_max_f32_e32 v54, 0, v59
	v_mul_f32_e32 v56, v56, v72
	v_mul_f32_e32 v52, v52, v72
	v_mul_f32_e32 v53, v53, v72
	v_mul_f32_e32 v54, v54, v72
	v_mul_f32_e32 v55, v55, v72
	v_mul_f32_e32 v56, v56, v56
	v_mul_f32_e32 v52, v52, v52
	v_mul_f32_e32 v53, v53, v53
	v_mul_f32_e32 v54, v54, v54
	v_mul_f32_e32 v55, v55, v55
	v_cvt_pk_bf16_f32 v52, v56, v52
	v_cvt_pk_bf16_f32 v53, v53, v54
	v_cvt_pk_bf16_f32 v54, v60, v57
	v_cvt_pk_bf16_f32 v55, v58, v55
	ds_read_b32 v56, v155 offset:576
	v_max_f32_e32 v44, 0, v44
	v_max_f32_e32 v45, 0, v45
	v_max_f32_e32 v46, 0, v46
	v_lshl_add_u64 v[68:69], v[148:149], 0, s[18:19]
	s_waitcnt lgkmcnt(0)
	v_mul_f32_e32 v44, v44, v56
	global_store_dwordx4 v[68:69], v[52:55], off offset:256 sc1
	v_max_f32_e32 v48, 0, v48
	v_mul_f32_e32 v45, v45, v56
	v_mul_f32_e32 v54, v44, v44
	v_max_f32_e32 v44, 0, v49
	v_mul_f32_e32 v46, v46, v56
	v_mul_f32_e32 v49, v45, v45
	v_max_f32_e32 v45, 0, v50
	v_mul_f32_e32 v50, v46, v46
	v_max_f32_e32 v46, 0, v51
	v_mul_f32_e32 v48, v48, v56
	v_mul_f32_e32 v44, v44, v56
	v_max_f32_e32 v47, 0, v47
	v_mul_f32_e32 v48, v48, v48
	v_mul_f32_e32 v44, v44, v44
	v_mul_f32_e32 v45, v45, v56
	v_mul_f32_e32 v46, v46, v56
	v_max_f32_e32 v36, 0, v36
	v_max_f32_e32 v37, 0, v37
	v_max_f32_e32 v38, 0, v38
	v_mul_f32_e32 v45, v45, v45
	v_mul_f32_e32 v47, v47, v56
	v_mul_f32_e32 v46, v46, v46
	v_cvt_pk_bf16_f32 v44, v48, v44
	v_add_co_u32_e32 v48, vcc, s61, v148
	v_mul_f32_e32 v47, v47, v47
	v_cvt_pk_bf16_f32 v45, v45, v46
	v_cvt_pk_bf16_f32 v46, v54, v49
	v_addc_co_u32_e32 v49, vcc, 0, v149, vcc
	v_mul_f32_e32 v36, v36, v56
	v_mul_f32_e32 v37, v37, v56
	v_mul_f32_e32 v38, v38, v56
	v_cvt_pk_bf16_f32 v47, v50, v47
	global_store_dwordx4 v[48:49], v[44:47], off sc1
	v_max_f32_e32 v40, 0, v40
	v_max_f32_e32 v39, 0, v39
	v_mul_f32_e32 v44, v36, v36
	v_max_f32_e32 v36, 0, v41
	v_mul_f32_e32 v41, v37, v37
	v_max_f32_e32 v37, 0, v42
	v_mul_f32_e32 v42, v38, v38
	v_max_f32_e32 v38, 0, v43
	v_mul_f32_e32 v40, v40, v56
	v_mul_f32_e32 v36, v36, v56
	v_mul_f32_e32 v37, v37, v56
	v_mul_f32_e32 v38, v38, v56
	v_mul_f32_e32 v39, v39, v56
	v_mul_f32_e32 v40, v40, v40
	v_mul_f32_e32 v36, v36, v36
	v_mul_f32_e32 v37, v37, v37
	v_mul_f32_e32 v38, v38, v38
	v_mul_f32_e32 v39, v39, v39
	v_cvt_pk_bf16_f32 v36, v40, v36
	v_cvt_pk_bf16_f32 v37, v37, v38
	v_cvt_pk_bf16_f32 v38, v44, v41
	v_cvt_pk_bf16_f32 v39, v42, v39
	ds_read_b32 v40, v155 offset:640
	v_max_f32_e32 v28, 0, v28
	v_max_f32_e32 v29, 0, v29
	v_max_f32_e32 v30, 0, v30
	v_lshl_add_u64 v[52:53], v[148:149], 0, s[20:21]
	s_waitcnt lgkmcnt(0)
	v_mul_f32_e32 v28, v28, v40
	global_store_dwordx4 v[52:53], v[36:39], off offset:256 sc1
	v_max_f32_e32 v32, 0, v32
	v_mul_f32_e32 v29, v29, v40
	v_mul_f32_e32 v38, v28, v28
	v_max_f32_e32 v28, 0, v33
	v_mul_f32_e32 v30, v30, v40
	v_mul_f32_e32 v33, v29, v29
	v_max_f32_e32 v29, 0, v34
	v_mul_f32_e32 v34, v30, v30
	v_max_f32_e32 v30, 0, v35
	v_mul_f32_e32 v32, v32, v40
	v_mul_f32_e32 v28, v28, v40
	v_max_f32_e32 v31, 0, v31
	v_mul_f32_e32 v32, v32, v32
	v_mul_f32_e32 v28, v28, v28
	v_mul_f32_e32 v29, v29, v40
	v_mul_f32_e32 v30, v30, v40
	v_max_f32_e32 v20, 0, v20
	v_max_f32_e32 v21, 0, v21
	v_max_f32_e32 v22, 0, v22
	v_mul_f32_e32 v29, v29, v29
	v_mul_f32_e32 v31, v31, v40
	v_mul_f32_e32 v30, v30, v30
	v_cvt_pk_bf16_f32 v28, v32, v28
	v_add_co_u32_e32 v32, vcc, s64, v148
	v_mul_f32_e32 v31, v31, v31
	v_cvt_pk_bf16_f32 v29, v29, v30
	v_cvt_pk_bf16_f32 v30, v38, v33
	v_addc_co_u32_e32 v33, vcc, 0, v149, vcc
	v_mul_f32_e32 v20, v20, v40
	v_mul_f32_e32 v21, v21, v40
	v_mul_f32_e32 v22, v22, v40
	v_cvt_pk_bf16_f32 v31, v34, v31
	global_store_dwordx4 v[32:33], v[28:31], off sc1
	v_max_f32_e32 v24, 0, v24
	v_max_f32_e32 v23, 0, v23
	v_mul_f32_e32 v28, v20, v20
	v_max_f32_e32 v20, 0, v25
	v_mul_f32_e32 v25, v21, v21
	v_max_f32_e32 v21, 0, v26
	v_mul_f32_e32 v26, v22, v22
	v_max_f32_e32 v22, 0, v27
	v_mul_f32_e32 v24, v24, v40
	v_mul_f32_e32 v20, v20, v40
	v_mul_f32_e32 v21, v21, v40
	v_mul_f32_e32 v22, v22, v40
	v_mul_f32_e32 v23, v23, v40
	v_mul_f32_e32 v24, v24, v24
	v_mul_f32_e32 v20, v20, v20
	v_mul_f32_e32 v21, v21, v21
	v_mul_f32_e32 v22, v22, v22
	v_mul_f32_e32 v23, v23, v23
	v_cvt_pk_bf16_f32 v20, v24, v20
	v_cvt_pk_bf16_f32 v21, v21, v22
	v_cvt_pk_bf16_f32 v22, v28, v25
	v_cvt_pk_bf16_f32 v23, v26, v23
	ds_read_b32 v24, v155 offset:704
	v_max_f32_e32 v12, 0, v12
	v_max_f32_e32 v13, 0, v13
	v_max_f32_e32 v14, 0, v14
	v_lshl_add_u64 v[36:37], v[148:149], 0, s[22:23]
	s_waitcnt lgkmcnt(0)
	v_mul_f32_e32 v12, v12, v24
	global_store_dwordx4 v[36:37], v[20:23], off offset:256 sc1
	v_max_f32_e32 v16, 0, v16
	v_mul_f32_e32 v13, v13, v24
	v_mul_f32_e32 v22, v12, v12
	v_max_f32_e32 v12, 0, v17
	v_mul_f32_e32 v14, v14, v24
	v_mul_f32_e32 v17, v13, v13
	v_max_f32_e32 v13, 0, v18
	v_mul_f32_e32 v18, v14, v14
	v_max_f32_e32 v14, 0, v19
	v_mul_f32_e32 v16, v16, v24
	v_mul_f32_e32 v12, v12, v24
	v_max_f32_e32 v15, 0, v15
	v_mul_f32_e32 v16, v16, v16
	v_mul_f32_e32 v12, v12, v12
	v_mul_f32_e32 v13, v13, v24
	v_mul_f32_e32 v14, v14, v24
	v_max_f32_e32 v4, 0, v4
	v_max_f32_e32 v5, 0, v5
	v_max_f32_e32 v6, 0, v6
	v_mul_f32_e32 v13, v13, v13
	v_mul_f32_e32 v15, v15, v24
	v_mul_f32_e32 v14, v14, v14
	v_cvt_pk_bf16_f32 v12, v16, v12
	v_add_co_u32_e32 v16, vcc, s65, v148
	v_mul_f32_e32 v15, v15, v15
	v_cvt_pk_bf16_f32 v13, v13, v14
	v_cvt_pk_bf16_f32 v14, v22, v17
	v_addc_co_u32_e32 v17, vcc, 0, v149, vcc
	v_mul_f32_e32 v4, v4, v24
	v_mul_f32_e32 v5, v5, v24
	v_mul_f32_e32 v6, v6, v24
	v_cvt_pk_bf16_f32 v15, v18, v15
	global_store_dwordx4 v[16:17], v[12:15], off sc1
	v_max_f32_e32 v7, 0, v7
	v_max_f32_e32 v8, 0, v8
	v_mul_f32_e32 v12, v4, v4
	v_max_f32_e32 v4, 0, v9
	v_mul_f32_e32 v9, v5, v5
	v_max_f32_e32 v5, 0, v10
	v_mul_f32_e32 v10, v6, v6
	v_max_f32_e32 v6, 0, v11
	v_mul_f32_e32 v4, v4, v24
	v_mul_f32_e32 v5, v5, v24
	v_mul_f32_e32 v6, v6, v24
	v_mul_f32_e32 v7, v7, v24
	v_lshl_add_u64 v[20:21], v[148:149], 0, s[24:25]
	v_mul_f32_e32 v8, v8, v24
	v_mul_f32_e32 v4, v4, v4
	v_mul_f32_e32 v5, v5, v5
	v_mul_f32_e32 v6, v6, v6
	v_mul_f32_e32 v7, v7, v7
	s_andn2_b64 vcc, exec, s[0:1]
	s_mov_b64 s[0:1], -1
	v_mul_f32_e32 v8, v8, v8
	v_cvt_pk_bf16_f32 v4, v8, v4
	v_cvt_pk_bf16_f32 v5, v5, v6
	v_cvt_pk_bf16_f32 v6, v12, v9
	v_cvt_pk_bf16_f32 v7, v10, v7
	global_store_dwordx4 v[20:21], v[4:7], off offset:256 sc1
	s_cbranch_vccnz .LBB0_812
	s_andn2_b64 vcc, exec, s[8:9]
	s_cbranch_vccnz .LBB0_811
	s_barrier
	s_branch .LBB0_811

.LBB0_1756:
	v_lshl_add_u32 v148, s34, 8, v152
	v_ashrrev_i32_e32 v149, 31, v148
	v_lshlrev_b64 v[150:151], 13, v[148:149]
	ds_read_b32 v149, v154
	v_lshl_or_b32 v146, s58, 8, v156
	v_max_f32_e32 v122, 0, v122
	v_ashrrev_i32_e32 v147, 31, v146
	v_max_f32_e32 v123, 0, v123
	v_max_f32_e32 v124, 0, v124
	v_lshl_add_u64 v[160:161], s[10:11], 0, v[150:151]
	v_lshlrev_b64 v[150:151], 1, v[146:147]
	s_waitcnt lgkmcnt(0)
	v_mul_f32_e32 v122, v122, v149
	v_lshl_add_u64 v[146:147], v[160:161], 0, v[150:151]
	v_mul_f32_e32 v160, v122, v122
	v_max_f32_e32 v122, 0, v127
	v_mul_f32_e32 v123, v123, v149
	v_mul_f32_e32 v124, v124, v149
	v_max_f32_e32 v126, 0, v126
	v_mul_f32_e32 v127, v123, v123
	v_max_f32_e32 v123, 0, v128
	v_mul_f32_e32 v128, v124, v124
	v_max_f32_e32 v124, 0, v129
	v_max_f32_e32 v125, 0, v125
	v_mul_f32_e32 v122, v122, v149
	v_max_f32_e32 v114, 0, v114
	v_max_f32_e32 v115, 0, v115
	v_max_f32_e32 v116, 0, v116
	v_mul_f32_e32 v126, v126, v149
	v_mul_f32_e32 v122, v122, v122
	v_mul_f32_e32 v123, v123, v149
	v_mul_f32_e32 v124, v124, v149
	v_mul_f32_e32 v125, v125, v149
	v_mul_f32_e32 v126, v126, v126
	v_mul_f32_e32 v123, v123, v123
	v_mul_f32_e32 v124, v124, v124
	v_mul_f32_e32 v125, v125, v125
	v_cvt_pk_bf16_f32 v122, v126, v122
	v_mul_f32_e32 v114, v114, v149
	v_mul_f32_e32 v115, v115, v149
	v_mul_f32_e32 v116, v116, v149
	v_cvt_pk_bf16_f32 v123, v123, v124
	v_cvt_pk_bf16_f32 v124, v160, v127
	v_cvt_pk_bf16_f32 v125, v128, v125
	global_store_dwordx4 v[146:147], v[122:125], off sc1
	v_max_f32_e32 v118, 0, v118
	v_max_f32_e32 v117, 0, v117
	v_mul_f32_e32 v122, v114, v114
	v_max_f32_e32 v114, 0, v119
	v_mul_f32_e32 v119, v115, v115
	v_max_f32_e32 v115, 0, v120
	v_mul_f32_e32 v120, v116, v116
	v_max_f32_e32 v116, 0, v121
	v_mul_f32_e32 v114, v114, v149
	v_mul_f32_e32 v115, v115, v149
	v_mul_f32_e32 v116, v116, v149
	v_mul_f32_e32 v118, v118, v149
	v_mul_f32_e32 v114, v114, v114
	v_mul_f32_e32 v115, v115, v115
	v_mul_f32_e32 v117, v117, v149
	v_mul_f32_e32 v116, v116, v116
	v_mul_f32_e32 v118, v118, v118
	v_mul_f32_e32 v117, v117, v117
	v_cvt_pk_bf16_f32 v114, v118, v114
	v_cvt_pk_bf16_f32 v115, v115, v116
	v_cvt_pk_bf16_f32 v116, v122, v119
	v_cvt_pk_bf16_f32 v117, v120, v117
	global_store_dwordx4 v[146:147], v[114:117], off offset:256 sc1
	ds_read_b32 v116, v154 offset:64
	v_max_f32_e32 v106, 0, v106
	v_max_f32_e32 v107, 0, v107
	v_max_f32_e32 v108, 0, v108
	s_waitcnt lgkmcnt(0)
	v_mul_f32_e32 v106, v106, v116
	v_or_b32_e32 v114, 16, v148
	v_mul_f32_e32 v117, v106, v106
	v_max_f32_e32 v106, 0, v111
	v_mul_f32_e32 v107, v107, v116
	v_mul_f32_e32 v108, v108, v116
	v_ashrrev_i32_e32 v115, 31, v114
	v_max_f32_e32 v110, 0, v110
	v_mul_f32_e32 v111, v107, v107
	v_max_f32_e32 v107, 0, v112
	v_mul_f32_e32 v112, v108, v108
	v_max_f32_e32 v108, 0, v113
	v_max_f32_e32 v109, 0, v109
	v_lshlrev_b64 v[114:115], 13, v[114:115]
	v_mul_f32_e32 v106, v106, v116
	v_max_f32_e32 v98, 0, v98
	v_max_f32_e32 v99, 0, v99
	v_max_f32_e32 v100, 0, v100
	v_lshl_add_u64 v[114:115], s[10:11], 0, v[114:115]
	v_mul_f32_e32 v110, v110, v116
	v_mul_f32_e32 v106, v106, v106
	v_mul_f32_e32 v107, v107, v116
	v_mul_f32_e32 v108, v108, v116
	v_mul_f32_e32 v109, v109, v116
	v_lshl_add_u64 v[114:115], v[114:115], 0, v[150:151]
	v_mul_f32_e32 v110, v110, v110
	v_mul_f32_e32 v107, v107, v107
	v_mul_f32_e32 v108, v108, v108
	v_mul_f32_e32 v109, v109, v109
	v_cvt_pk_bf16_f32 v106, v110, v106
	v_mul_f32_e32 v98, v98, v116
	v_mul_f32_e32 v99, v99, v116
	v_mul_f32_e32 v100, v100, v116
	v_cvt_pk_bf16_f32 v107, v107, v108
	v_cvt_pk_bf16_f32 v108, v117, v111
	v_cvt_pk_bf16_f32 v109, v112, v109
	global_store_dwordx4 v[114:115], v[106:109], off sc1
	v_max_f32_e32 v102, 0, v102
	v_max_f32_e32 v101, 0, v101
	v_mul_f32_e32 v106, v98, v98
	v_max_f32_e32 v98, 0, v103
	v_mul_f32_e32 v103, v99, v99
	v_max_f32_e32 v99, 0, v104
	v_mul_f32_e32 v104, v100, v100
	v_max_f32_e32 v100, 0, v105
	v_mul_f32_e32 v98, v98, v116
	v_mul_f32_e32 v99, v99, v116
	v_mul_f32_e32 v100, v100, v116
	v_mul_f32_e32 v102, v102, v116
	v_mul_f32_e32 v98, v98, v98
	v_mul_f32_e32 v99, v99, v99
	v_mul_f32_e32 v101, v101, v116
	v_mul_f32_e32 v100, v100, v100
	v_mul_f32_e32 v102, v102, v102
	v_mul_f32_e32 v101, v101, v101
	v_cvt_pk_bf16_f32 v98, v102, v98
	v_cvt_pk_bf16_f32 v99, v99, v100
	v_cvt_pk_bf16_f32 v100, v106, v103
	v_cvt_pk_bf16_f32 v101, v104, v101
	global_store_dwordx4 v[114:115], v[98:101], off offset:256 sc1
	ds_read_b32 v100, v154 offset:128
	v_max_f32_e32 v90, 0, v90
	v_max_f32_e32 v91, 0, v91
	v_max_f32_e32 v92, 0, v92
	s_waitcnt lgkmcnt(0)
	v_mul_f32_e32 v90, v90, v100
	v_or_b32_e32 v98, 32, v148
	v_mul_f32_e32 v101, v90, v90
	v_max_f32_e32 v90, 0, v95
	v_mul_f32_e32 v91, v91, v100
	v_mul_f32_e32 v92, v92, v100
	v_ashrrev_i32_e32 v99, 31, v98
	v_max_f32_e32 v94, 0, v94
	v_mul_f32_e32 v95, v91, v91
	v_max_f32_e32 v91, 0, v96
	v_mul_f32_e32 v96, v92, v92
	v_max_f32_e32 v92, 0, v97
	v_max_f32_e32 v93, 0, v93
	v_lshlrev_b64 v[98:99], 13, v[98:99]
	v_mul_f32_e32 v90, v90, v100
	v_max_f32_e32 v82, 0, v82
	v_max_f32_e32 v83, 0, v83
	v_max_f32_e32 v84, 0, v84
	v_lshl_add_u64 v[98:99], s[10:11], 0, v[98:99]
	v_mul_f32_e32 v94, v94, v100
	v_mul_f32_e32 v90, v90, v90
	v_mul_f32_e32 v91, v91, v100
	v_mul_f32_e32 v92, v92, v100
	v_mul_f32_e32 v93, v93, v100
	v_lshl_add_u64 v[98:99], v[98:99], 0, v[150:151]
	v_mul_f32_e32 v94, v94, v94
	v_mul_f32_e32 v91, v91, v91
	v_mul_f32_e32 v92, v92, v92
	v_mul_f32_e32 v93, v93, v93
	v_cvt_pk_bf16_f32 v90, v94, v90
	v_mul_f32_e32 v82, v82, v100
	v_mul_f32_e32 v83, v83, v100
	v_mul_f32_e32 v84, v84, v100
	v_cvt_pk_bf16_f32 v91, v91, v92
	v_cvt_pk_bf16_f32 v92, v101, v95
	v_cvt_pk_bf16_f32 v93, v96, v93
	global_store_dwordx4 v[98:99], v[90:93], off sc1
	v_max_f32_e32 v86, 0, v86
	v_max_f32_e32 v85, 0, v85
	v_mul_f32_e32 v90, v82, v82
	v_max_f32_e32 v82, 0, v87
	v_mul_f32_e32 v87, v83, v83
	v_max_f32_e32 v83, 0, v88
	v_mul_f32_e32 v88, v84, v84
	v_max_f32_e32 v84, 0, v89
	v_mul_f32_e32 v82, v82, v100
	v_mul_f32_e32 v83, v83, v100
	v_mul_f32_e32 v84, v84, v100
	v_mul_f32_e32 v86, v86, v100
	v_mul_f32_e32 v82, v82, v82
	v_mul_f32_e32 v83, v83, v83
	v_mul_f32_e32 v85, v85, v100
	v_mul_f32_e32 v84, v84, v84
	v_mul_f32_e32 v86, v86, v86
	v_mul_f32_e32 v85, v85, v85
	v_cvt_pk_bf16_f32 v82, v86, v82
	v_cvt_pk_bf16_f32 v83, v83, v84
	v_cvt_pk_bf16_f32 v84, v90, v87
	v_cvt_pk_bf16_f32 v85, v88, v85
	global_store_dwordx4 v[98:99], v[82:85], off offset:256 sc1
	ds_read_b32 v84, v154 offset:192
	v_max_f32_e32 v74, 0, v74
	v_max_f32_e32 v75, 0, v75
	v_max_f32_e32 v76, 0, v76
	s_waitcnt lgkmcnt(0)
	v_mul_f32_e32 v74, v74, v84
	v_or_b32_e32 v82, 48, v148
	v_mul_f32_e32 v85, v74, v74
	v_max_f32_e32 v74, 0, v79
	v_mul_f32_e32 v75, v75, v84
	v_mul_f32_e32 v76, v76, v84
	v_ashrrev_i32_e32 v83, 31, v82
	v_max_f32_e32 v78, 0, v78
	v_mul_f32_e32 v79, v75, v75
	v_max_f32_e32 v75, 0, v80
	v_mul_f32_e32 v80, v76, v76
	v_max_f32_e32 v76, 0, v81
	v_max_f32_e32 v77, 0, v77
	v_lshlrev_b64 v[82:83], 13, v[82:83]
	v_mul_f32_e32 v74, v74, v84
	v_max_f32_e32 v66, 0, v66
	v_max_f32_e32 v67, 0, v67
	v_max_f32_e32 v68, 0, v68
	v_lshl_add_u64 v[82:83], s[10:11], 0, v[82:83]
	v_mul_f32_e32 v78, v78, v84
	v_mul_f32_e32 v74, v74, v74
	v_mul_f32_e32 v75, v75, v84
	v_mul_f32_e32 v76, v76, v84
	v_mul_f32_e32 v77, v77, v84
	v_lshl_add_u64 v[82:83], v[82:83], 0, v[150:151]
	v_mul_f32_e32 v78, v78, v78
	v_mul_f32_e32 v75, v75, v75
	v_mul_f32_e32 v76, v76, v76
	v_mul_f32_e32 v77, v77, v77
	v_cvt_pk_bf16_f32 v74, v78, v74
	v_mul_f32_e32 v66, v66, v84
	v_mul_f32_e32 v67, v67, v84
	v_mul_f32_e32 v68, v68, v84
	v_cvt_pk_bf16_f32 v75, v75, v76
	v_cvt_pk_bf16_f32 v76, v85, v79
	v_cvt_pk_bf16_f32 v77, v80, v77
	global_store_dwordx4 v[82:83], v[74:77], off sc1
	v_max_f32_e32 v70, 0, v70
	v_max_f32_e32 v69, 0, v69
	v_mul_f32_e32 v74, v66, v66
	v_max_f32_e32 v66, 0, v71
	v_mul_f32_e32 v71, v67, v67
	v_max_f32_e32 v67, 0, v72
	v_mul_f32_e32 v72, v68, v68
	v_max_f32_e32 v68, 0, v73
	v_mul_f32_e32 v70, v70, v84
	v_mul_f32_e32 v66, v66, v84
	v_mul_f32_e32 v67, v67, v84
	v_mul_f32_e32 v68, v68, v84
	v_mul_f32_e32 v69, v69, v84
	v_mul_f32_e32 v70, v70, v70
	v_mul_f32_e32 v66, v66, v66
	v_mul_f32_e32 v67, v67, v67
	v_mul_f32_e32 v68, v68, v68
	v_mul_f32_e32 v69, v69, v69
	v_cvt_pk_bf16_f32 v66, v70, v66
	v_cvt_pk_bf16_f32 v67, v67, v68
	v_cvt_pk_bf16_f32 v68, v74, v71
	v_cvt_pk_bf16_f32 v69, v72, v69
	ds_read_b32 v70, v155
	v_max_f32_e32 v58, 0, v58
	v_max_f32_e32 v59, 0, v59
	v_max_f32_e32 v60, 0, v60
	s_waitcnt lgkmcnt(0)
	v_mul_f32_e32 v58, v58, v70
	global_store_dwordx4 v[82:83], v[66:69], off offset:256 sc1
	v_max_f32_e32 v62, 0, v62
	v_mul_f32_e32 v59, v59, v70
	v_mul_f32_e32 v68, v58, v58
	v_max_f32_e32 v58, 0, v63
	v_mul_f32_e32 v60, v60, v70
	v_mul_f32_e32 v63, v59, v59
	v_max_f32_e32 v59, 0, v64
	v_mul_f32_e32 v64, v60, v60
	v_max_f32_e32 v60, 0, v65
	v_mul_f32_e32 v62, v62, v70
	v_mul_f32_e32 v58, v58, v70
	v_max_f32_e32 v61, 0, v61
	v_mul_f32_e32 v62, v62, v62
	v_mul_f32_e32 v58, v58, v58
	v_mul_f32_e32 v59, v59, v70
	v_mul_f32_e32 v60, v60, v70
	v_max_f32_e32 v50, 0, v50
	v_max_f32_e32 v51, 0, v51
	v_max_f32_e32 v52, 0, v52
	v_mul_f32_e32 v59, v59, v59
	v_mul_f32_e32 v61, v61, v70
	v_mul_f32_e32 v60, v60, v60
	v_cvt_pk_bf16_f32 v58, v62, v58
	v_add_co_u32_e32 v62, vcc, s52, v146
	v_mul_f32_e32 v61, v61, v61
	v_cvt_pk_bf16_f32 v59, v59, v60
	v_cvt_pk_bf16_f32 v60, v68, v63
	v_addc_co_u32_e32 v63, vcc, 0, v147, vcc
	v_mul_f32_e32 v50, v50, v70
	v_mul_f32_e32 v51, v51, v70
	v_mul_f32_e32 v52, v52, v70
	v_cvt_pk_bf16_f32 v61, v64, v61
	global_store_dwordx4 v[62:63], v[58:61], off sc1
	v_max_f32_e32 v54, 0, v54
	v_max_f32_e32 v53, 0, v53
	v_mul_f32_e32 v58, v50, v50
	v_max_f32_e32 v50, 0, v55
	v_mul_f32_e32 v55, v51, v51
	v_max_f32_e32 v51, 0, v56
	v_mul_f32_e32 v56, v52, v52
	v_max_f32_e32 v52, 0, v57
	v_mul_f32_e32 v54, v54, v70
	v_mul_f32_e32 v50, v50, v70
	v_mul_f32_e32 v51, v51, v70
	v_mul_f32_e32 v52, v52, v70
	v_mul_f32_e32 v53, v53, v70
	v_mul_f32_e32 v54, v54, v54
	v_mul_f32_e32 v50, v50, v50
	v_mul_f32_e32 v51, v51, v51
	v_mul_f32_e32 v52, v52, v52
	v_mul_f32_e32 v53, v53, v53
	v_cvt_pk_bf16_f32 v50, v54, v50
	v_cvt_pk_bf16_f32 v51, v51, v52
	v_cvt_pk_bf16_f32 v52, v58, v55
	v_cvt_pk_bf16_f32 v53, v56, v53
	ds_read_b32 v54, v154 offset:576
	v_max_f32_e32 v42, 0, v42
	v_max_f32_e32 v43, 0, v43
	v_max_f32_e32 v44, 0, v44
	v_lshl_add_u64 v[66:67], v[146:147], 0, s[16:17]
	s_waitcnt lgkmcnt(0)
	v_mul_f32_e32 v42, v42, v54
	global_store_dwordx4 v[66:67], v[50:53], off offset:256 sc1
	v_max_f32_e32 v46, 0, v46
	v_mul_f32_e32 v43, v43, v54
	v_mul_f32_e32 v52, v42, v42
	v_max_f32_e32 v42, 0, v47
	v_mul_f32_e32 v44, v44, v54
	v_mul_f32_e32 v47, v43, v43
	v_max_f32_e32 v43, 0, v48
	v_mul_f32_e32 v48, v44, v44
	v_max_f32_e32 v44, 0, v49
	v_mul_f32_e32 v46, v46, v54
	v_mul_f32_e32 v42, v42, v54
	v_max_f32_e32 v45, 0, v45
	v_mul_f32_e32 v46, v46, v46
	v_mul_f32_e32 v42, v42, v42
	v_mul_f32_e32 v43, v43, v54
	v_mul_f32_e32 v44, v44, v54
	v_max_f32_e32 v34, 0, v34
	v_max_f32_e32 v35, 0, v35
	v_max_f32_e32 v36, 0, v36
	v_mul_f32_e32 v43, v43, v43
	v_mul_f32_e32 v45, v45, v54
	v_mul_f32_e32 v44, v44, v44
	v_cvt_pk_bf16_f32 v42, v46, v42
	v_add_co_u32_e32 v46, vcc, s53, v146
	v_mul_f32_e32 v45, v45, v45
	v_cvt_pk_bf16_f32 v43, v43, v44
	v_cvt_pk_bf16_f32 v44, v52, v47
	v_addc_co_u32_e32 v47, vcc, 0, v147, vcc
	v_mul_f32_e32 v34, v34, v54
	v_mul_f32_e32 v35, v35, v54
	v_mul_f32_e32 v36, v36, v54
	v_cvt_pk_bf16_f32 v45, v48, v45
	global_store_dwordx4 v[46:47], v[42:45], off sc1
	v_max_f32_e32 v38, 0, v38
	v_max_f32_e32 v37, 0, v37
	v_mul_f32_e32 v42, v34, v34
	v_max_f32_e32 v34, 0, v39
	v_mul_f32_e32 v39, v35, v35
	v_max_f32_e32 v35, 0, v40
	v_mul_f32_e32 v40, v36, v36
	v_max_f32_e32 v36, 0, v41
	v_mul_f32_e32 v38, v38, v54
	v_mul_f32_e32 v34, v34, v54
	v_mul_f32_e32 v35, v35, v54
	v_mul_f32_e32 v36, v36, v54
	v_mul_f32_e32 v37, v37, v54
	v_mul_f32_e32 v38, v38, v38
	v_mul_f32_e32 v34, v34, v34
	v_mul_f32_e32 v35, v35, v35
	v_mul_f32_e32 v36, v36, v36
	v_mul_f32_e32 v37, v37, v37
	v_cvt_pk_bf16_f32 v34, v38, v34
	v_cvt_pk_bf16_f32 v35, v35, v36
	v_cvt_pk_bf16_f32 v36, v42, v39
	v_cvt_pk_bf16_f32 v37, v40, v37
	ds_read_b32 v38, v154 offset:640
	v_max_f32_e32 v26, 0, v26
	v_max_f32_e32 v27, 0, v27
	v_max_f32_e32 v28, 0, v28
	v_lshl_add_u64 v[50:51], v[146:147], 0, s[18:19]
	s_waitcnt lgkmcnt(0)
	v_mul_f32_e32 v26, v26, v38
	global_store_dwordx4 v[50:51], v[34:37], off offset:256 sc1
	v_max_f32_e32 v30, 0, v30
	v_mul_f32_e32 v27, v27, v38
	v_mul_f32_e32 v36, v26, v26
	v_max_f32_e32 v26, 0, v31
	v_mul_f32_e32 v28, v28, v38
	v_mul_f32_e32 v31, v27, v27
	v_max_f32_e32 v27, 0, v32
	v_mul_f32_e32 v32, v28, v28
	v_max_f32_e32 v28, 0, v33
	v_mul_f32_e32 v30, v30, v38
	v_mul_f32_e32 v26, v26, v38
	v_max_f32_e32 v29, 0, v29
	v_mul_f32_e32 v30, v30, v30
	v_mul_f32_e32 v26, v26, v26
	v_mul_f32_e32 v27, v27, v38
	v_mul_f32_e32 v28, v28, v38
	v_max_f32_e32 v18, 0, v18
	v_max_f32_e32 v19, 0, v19
	v_max_f32_e32 v20, 0, v20
	v_mul_f32_e32 v27, v27, v27
	v_mul_f32_e32 v29, v29, v38
	v_mul_f32_e32 v28, v28, v28
	v_cvt_pk_bf16_f32 v26, v30, v26
	v_add_co_u32_e32 v30, vcc, s54, v146
	v_mul_f32_e32 v29, v29, v29
	v_cvt_pk_bf16_f32 v27, v27, v28
	v_cvt_pk_bf16_f32 v28, v36, v31
	v_addc_co_u32_e32 v31, vcc, 0, v147, vcc
	v_mul_f32_e32 v18, v18, v38
	v_mul_f32_e32 v19, v19, v38
	v_mul_f32_e32 v20, v20, v38
	v_cvt_pk_bf16_f32 v29, v32, v29
	global_store_dwordx4 v[30:31], v[26:29], off sc1
	v_max_f32_e32 v22, 0, v22
	v_max_f32_e32 v21, 0, v21
	v_mul_f32_e32 v26, v18, v18
	v_max_f32_e32 v18, 0, v23
	v_mul_f32_e32 v23, v19, v19
	v_max_f32_e32 v19, 0, v24
	v_mul_f32_e32 v24, v20, v20
	v_max_f32_e32 v20, 0, v25
	v_mul_f32_e32 v22, v22, v38
	v_mul_f32_e32 v18, v18, v38
	v_mul_f32_e32 v19, v19, v38
	v_mul_f32_e32 v20, v20, v38
	v_mul_f32_e32 v21, v21, v38
	v_mul_f32_e32 v22, v22, v22
	v_mul_f32_e32 v18, v18, v18
	v_mul_f32_e32 v19, v19, v19
	v_mul_f32_e32 v20, v20, v20
	v_mul_f32_e32 v21, v21, v21
	v_cvt_pk_bf16_f32 v18, v22, v18
	v_cvt_pk_bf16_f32 v19, v19, v20
	v_cvt_pk_bf16_f32 v20, v26, v23
	v_cvt_pk_bf16_f32 v21, v24, v21
	ds_read_b32 v22, v154 offset:704
	v_max_f32_e32 v10, 0, v10
	v_max_f32_e32 v11, 0, v11
	v_max_f32_e32 v12, 0, v12
	v_lshl_add_u64 v[34:35], v[146:147], 0, s[20:21]
	s_waitcnt lgkmcnt(0)
	v_mul_f32_e32 v10, v10, v22
	global_store_dwordx4 v[34:35], v[18:21], off offset:256 sc1
	v_max_f32_e32 v14, 0, v14
	v_mul_f32_e32 v11, v11, v22
	v_mul_f32_e32 v20, v10, v10
	v_max_f32_e32 v10, 0, v15
	v_mul_f32_e32 v12, v12, v22
	v_mul_f32_e32 v15, v11, v11
	v_max_f32_e32 v11, 0, v16
	v_mul_f32_e32 v16, v12, v12
	v_max_f32_e32 v12, 0, v17
	v_mul_f32_e32 v14, v14, v22
	v_mul_f32_e32 v10, v10, v22
	v_max_f32_e32 v13, 0, v13
	v_mul_f32_e32 v14, v14, v14
	v_mul_f32_e32 v10, v10, v10
	v_mul_f32_e32 v11, v11, v22
	v_mul_f32_e32 v12, v12, v22
	v_max_f32_e32 v2, 0, v2
	v_max_f32_e32 v3, 0, v3
	v_max_f32_e32 v4, 0, v4
	v_mul_f32_e32 v11, v11, v11
	v_mul_f32_e32 v13, v13, v22
	v_mul_f32_e32 v12, v12, v12
	v_cvt_pk_bf16_f32 v10, v14, v10
	v_add_co_u32_e32 v14, vcc, s55, v146
	v_mul_f32_e32 v13, v13, v13
	v_cvt_pk_bf16_f32 v11, v11, v12
	v_cvt_pk_bf16_f32 v12, v20, v15
	v_addc_co_u32_e32 v15, vcc, 0, v147, vcc
	v_mul_f32_e32 v2, v2, v22
	v_mul_f32_e32 v3, v3, v22
	v_mul_f32_e32 v4, v4, v22
	v_cvt_pk_bf16_f32 v13, v16, v13
	global_store_dwordx4 v[14:15], v[10:13], off sc1
	v_max_f32_e32 v5, 0, v5
	v_max_f32_e32 v6, 0, v6
	v_mul_f32_e32 v10, v2, v2
	v_max_f32_e32 v2, 0, v7
	v_mul_f32_e32 v7, v3, v3
	v_max_f32_e32 v3, 0, v8
	v_mul_f32_e32 v8, v4, v4
	v_max_f32_e32 v4, 0, v9
	v_mul_f32_e32 v2, v2, v22
	v_mul_f32_e32 v3, v3, v22
	v_mul_f32_e32 v4, v4, v22
	v_mul_f32_e32 v5, v5, v22
	v_lshl_add_u64 v[18:19], v[146:147], 0, s[22:23]
	v_mul_f32_e32 v6, v6, v22
	v_mul_f32_e32 v2, v2, v2
	v_mul_f32_e32 v3, v3, v3
	v_mul_f32_e32 v4, v4, v4
	v_mul_f32_e32 v5, v5, v5
	s_andn2_b64 vcc, exec, s[0:1]
	s_mov_b64 s[0:1], -1
	v_mul_f32_e32 v6, v6, v6
	v_cvt_pk_bf16_f32 v2, v6, v2
	v_cvt_pk_bf16_f32 v3, v3, v4
	v_cvt_pk_bf16_f32 v4, v10, v7
	v_cvt_pk_bf16_f32 v5, v8, v5
	global_store_dwordx4 v[18:19], v[2:5], off offset:256 sc1
	s_cbranch_vccnz .LBB0_1745
	s_andn2_b64 vcc, exec, s[8:9]
	s_cbranch_vccnz .LBB0_1744
	s_barrier
	s_branch .LBB0_1744
